# FoX: V^T LDS tile stored with the two middle 4-key blocks of every 16-key group swapped (2x ds_write_b64 per row piece) so each PV A-fragment is one ds_read_b128 instead of a 2-way bank-conflicted ds_
# baseline (speedup 1.0000x reference)
; DI void fox_attn(const Params& P, int bh, int qb, unsigned char* smem, int tt) {
;     ...
;     const float cq = cf[q] * L2E;
;     float m = -1e30f, l = 0.f;
;     f32x16 O[2];
; #pragma unroll
;     for (int e = 0; e < 16; ++e) { O[0][e] = 0.f; O[1][e] = 0.f; }
;     const int ntiles = 2 * qb + 2;
;     const int srow = tid >> 3, scol = (tid & 7) * 8;
;     const bf16_t* kg = fqk + ((size_t)b * TSEQ + srow) * 1024 + 512 + hh * 64 + scol;
;     const bf16_t* vg = vT + (size_t)srow * TSEQ + scol;
;     u32x4 rk0, rk1, rv0, rv1; float rc = 0.f;
;     rk0 = *(const u32x4*)kg; rk1 = *(const u32x4*)(kg + 32 * 1024);
;     rv0 = *(const u32x4*)vg; rv1 = *(const u32x4*)(vg + 32 * TSEQ);
;     if (tid < 64) rc = cf[tid] * L2E;
;     {
;         bf16_t* Ks = (bf16_t*)smem; bf16_t* VTs = Ks + 64 * 72; float* cks = (float*)(smem + 2 * 64 * 72 * 2);
;         *(u32x4*)(Ks + srow * 72 + scol) = rk0; *(u32x4*)(Ks + (srow + 32) * 72 + scol) = rk1;
;         *(u32x4*)(VTs + srow * 72 + scol) = rv0; *(u32x4*)(VTs + (srow + 32) * 72 + scol) = rv1;
;         if (tid < 64) cks[tid] = rc;
;     }
;     __syncthreads();
.LBB0_542:
	s_or_b64 exec, exec, s[2:3]
	v_mul_u32_u24_e32 v0, 0x48, v2
	v_lshlrev_b32_e32 v119, 1, v0
	v_add3_u32 v0, v131, v119, v104
	s_waitcnt vmcnt(4)
	ds_write_b128 v0, v[82:85]
	s_waitcnt vmcnt(3)
	ds_write_b128 v0, v[86:89] offset:4608
	v_and_b32_e32 v187, 16, v104
	v_lshrrev_b32_e32 v187, 1, v187
	v_sub_u32_e32 v186, v0, v187
	s_waitcnt vmcnt(1)
	ds_write_b64 v186, v[90:91] offset:9216
	ds_write_b64 v186, v[92:93] offset:9232
	s_waitcnt vmcnt(0)
	ds_write_b64 v186, v[94:95] offset:13824
	ds_write_b64 v186, v[96:97] offset:13840
	s_and_saveexec_b64 s[2:3], s[0:1]
	v_lshl_add_u32 v0, v130, 2, v131
	ds_write_b32 v0, v118 offset:18432
	s_or_b64 exec, exec, s[2:3]
	v_lshlrev_b32_e32 v0, 3, v23
	v_mul_f32_e32 v121, 0x3fb8aa3b, v3
	v_lshlrev_b32_e32 v105, 2, v23
	v_lshlrev_b32_e32 v3, 2, v14
	v_lshl_add_u32 v125, v0, 1, v131
	v_sub_u32_e32 v126, 0, v0
	v_add_u32_e32 v0, v9, v22
	v_xor_b32_e32 v99, 0x80, v3
	v_sub_u32_e32 v0, v0, v105
	v_lshlrev_b32_e32 v3, 7, v8
	v_sub_u32_e32 v0, v0, v3
	v_lshlrev_b64 v[4:5], 22, v[4:5]
	v_add_u32_e32 v127, 0x780, v0
	v_lshl_or_b32 v0, v2, 11, v4
	v_lshlrev_b32_e32 v2, 1, v12
	v_and_b32_e32 v3, 7, v10
	v_and_b32_e32 v2, 0x380, v2
	v_lshlrev_b32_e32 v3, 4, v3
	v_or3_b32 v4, v0, v2, v3
	v_mov_b32_e32 v14, v1
	v_mov_b32_e32 v15, v1
	v_lshlrev_b64 v[100:101], 10, v[6:7]
	v_lshlrev_b32_e32 v122, 1, v11
	v_mul_u32_u24_e32 v124, 0x48, v22
	v_lshl_add_u64 v[108:109], s[10:11], 0, v[4:5]
	v_mov_b32_e32 v0, v1
	v_mov_b32_e32 v2, v1
	v_mov_b32_e32 v3, v1
	v_mov_b32_e32 v4, v1
	v_mov_b32_e32 v5, v1
	v_mov_b32_e32 v6, v1
	v_mov_b32_e32 v7, v1
	v_mov_b32_e32 v8, v1
	v_mov_b32_e32 v9, v1
	v_mov_b32_e32 v10, v1
	v_mov_b32_e32 v11, v1
	v_mov_b32_e32 v12, v1
	v_mov_b32_e32 v13, v1
	v_mov_b64_e32 v[32:33], v[14:15]
	v_mov_b64_e32 v[30:31], v[12:13]
	v_mov_b64_e32 v[28:29], v[10:11]
	v_mov_b64_e32 v[26:27], v[8:9]
	v_mov_b64_e32 v[24:25], v[6:7]
	v_mov_b64_e32 v[22:23], v[4:5]
	v_mov_b64_e32 v[20:21], v[2:3]
	v_mov_b64_e32 v[18:19], v[0:1]
	v_mov_b64_e32 v[16:17], v[14:15]
	v_add_u32_e32 v123, 2, v122
	s_mov_b32 s47, 0
	v_mov_b32_e32 v120, 0
	v_mov_b32_e32 v128, 0xf149f2ca
	s_mov_b32 s34, 64
	s_mov_b64 s[30:31], 0
	v_mov_b64_e32 v[14:15], v[12:13]
	v_mov_b64_e32 v[12:13], v[10:11]
	v_mov_b64_e32 v[10:11], v[8:9]
	v_mov_b64_e32 v[8:9], v[6:7]
	v_mov_b64_e32 v[6:7], v[4:5]
	v_mov_b64_e32 v[4:5], v[2:3]
	v_mov_b64_e32 v[2:3], v[0:1]
	s_waitcnt lgkmcnt(0)
	s_barrier
	s_branch .LBB0_546

; DI void fox_attn(const Params& P, int bh, int qb, unsigned char* smem, int tt) {
;     ...
;         {
;             const float sh = cq - m;
;             const f32x2v sh2 = {sh, sh};
;             f32x2v rs2 = {0.f, 0.f};
; #pragma unroll
;             for (int mt = 0; mt < 2; ++mt)
; #pragma unroll
;                 for (int p2 = 0; p2 < 8; ++p2) {
;                     const f32x2v sv = {sacc[mt][2 * p2], sacc[mt][2 * p2 + 1]};
;                     const f32x2v t = sv + sh2;
;                     f32x2v pp; pp.x = __builtin_amdgcn_exp2f(t.x); pp.y = __builtin_amdgcn_exp2f(t.y);
;                     sacc[mt][2 * p2] = pp.x; sacc[mt][2 * p2 + 1] = pp.y;
;                     rs2 = rs2 + pp;
;                 }
;             l += rs2.x + rs2.y;
;         }
;         {
;             u32x4 vw[2][2][2];
; #pragma unroll
;             for (int mt = 0; mt < 2; ++mt)
; #pragma unroll
;                 for (int s = 0; s < 2; ++s)
; #pragma unroll
;                     for (int dt = 0; dt < 2; ++dt) {
;                         const bf16_t* vp = VTs + (dt * 32 + r) * 72 + mt * 32 + 16 * s + 4 * h2;
;                         const u32x2 lo = *(const u32x2*)vp, hi = *(const u32x2*)(vp + 8);
;                         vw[mt][s][dt].x = lo.x; vw[mt][s][dt].y = lo.y; vw[mt][s][dt].z = hi.x; vw[mt][s][dt].w = hi.y;
;                     }
;             u32x4 pw[2][2];
; #pragma unroll
;             for (int mt = 0; mt < 2; ++mt)
; #pragma unroll
;                 for (int s = 0; s < 2; ++s) {
;                     pw[mt][s].x = pack2(sacc[mt][8 * s + 0], sacc[mt][8 * s + 1]); pw[mt][s].y = pack2(sacc[mt][8 * s + 2], sacc[mt][8 * s + 3]);
;                     pw[mt][s].z = pack2(sacc[mt][8 * s + 4], sacc[mt][8 * s + 5]); pw[mt][s].w = pack2(sacc[mt][8 * s + 6], sacc[mt][8 * s + 7]);
;                 }
;             __builtin_amdgcn_sched_barrier(0);
; #pragma unroll
;             for (int mt = 0; mt < 2; ++mt)
; #pragma unroll
;                 for (int s = 0; s < 2; ++s) {
;                     const bf16x8 pf = __builtin_bit_cast(bf16x8, pw[mt][s]);
;                     O[0] = MFMA32(__builtin_bit_cast(bf16x8, vw[mt][s][0]), pf, O[0]);
;                     O[1] = MFMA32(__builtin_bit_cast(bf16x8, vw[mt][s][1]), pf, O[1]);
;                 }
;         }
;         if (more) {
;             unsigned char* bufn = smem + ((kt + 1) & 1) * BUFB;
.LBB0_554:
	v_sub_f32_e32 v132, v121, v128
	v_pk_add_f32 v[44:45], v[110:111], v[132:133] op_sel_hi:[1,0]
	v_lshl_add_u32 v188, v124, 1, v0
	v_lshlrev_b32_e32 v110, 1, v124
	v_add3_u32 v0, v0, v126, v110
	v_add_u32_e32 v129, 0x2000, v0
	v_add_u32_e32 v0, 0x3000, v0
	v_pk_add_f32 v[46:47], v[50:51], v[132:133] op_sel_hi:[1,0]
	v_pk_add_f32 v[48:49], v[114:115], v[132:133] op_sel_hi:[1,0]
	v_pk_add_f32 v[50:51], v[54:55], v[132:133] op_sel_hi:[1,0]
	v_pk_add_f32 v[54:55], v[112:113], v[132:133] op_sel_hi:[1,0]
	v_pk_add_f32 v[58:59], v[58:59], v[132:133] op_sel_hi:[1,0]
	v_pk_add_f32 v[64:65], v[116:117], v[132:133] op_sel_hi:[1,0]
	v_pk_add_f32 v[56:57], v[56:57], v[132:133] op_sel_hi:[1,0]
	v_pk_add_f32 v[62:63], v[62:63], v[132:133] op_sel_hi:[1,0]
	v_pk_add_f32 v[52:53], v[52:53], v[132:133] op_sel_hi:[1,0]
	v_pk_add_f32 v[60:61], v[60:61], v[132:133] op_sel_hi:[1,0]
	v_pk_add_f32 v[38:39], v[38:39], v[132:133] op_sel_hi:[1,0]
	v_pk_add_f32 v[42:43], v[42:43], v[132:133] op_sel_hi:[1,0]
	v_pk_add_f32 v[36:37], v[36:37], v[132:133] op_sel_hi:[1,0]
	v_pk_add_f32 v[40:41], v[40:41], v[132:133] op_sel_hi:[1,0]
	v_pk_add_f32 v[34:35], v[34:35], v[132:133] op_sel_hi:[1,0]
	ds_read_b128 v[110:113], v188 offset:9216
	ds_read_b128 v[114:117], v188 offset:9248
	ds_read_b128 v[132:135], v188 offset:13824
	ds_read_b128 v[136:139], v188 offset:13856
	ds_read_b128 v[140:143], v188 offset:9280
	ds_read_b128 v[144:147], v188 offset:13888
	ds_read_b128 v[148:151], v188 offset:9312
	ds_read_b128 v[152:155], v188 offset:13920
	v_exp_f32_e32 v44, v44
	v_exp_f32_e32 v45, v45
	v_exp_f32_e32 v46, v46
	v_exp_f32_e32 v47, v47
	v_exp_f32_e32 v48, v48
	v_exp_f32_e32 v49, v49
	v_exp_f32_e32 v50, v50
	v_exp_f32_e32 v51, v51
	v_exp_f32_e32 v54, v54
	v_exp_f32_e32 v55, v55
	v_exp_f32_e32 v58, v58
	v_exp_f32_e32 v59, v59
	v_exp_f32_e32 v64, v64
	v_exp_f32_e32 v65, v65
	v_exp_f32_e32 v56, v56
	v_exp_f32_e32 v57, v57
	v_exp_f32_e32 v62, v62
	v_exp_f32_e32 v63, v63
	v_exp_f32_e32 v52, v52
	v_exp_f32_e32 v53, v53
	v_exp_f32_e32 v60, v60
	v_exp_f32_e32 v61, v61
	v_exp_f32_e32 v38, v38
	v_exp_f32_e32 v39, v39
	v_exp_f32_e32 v42, v42
	v_exp_f32_e32 v43, v43
	v_exp_f32_e32 v36, v36
	v_exp_f32_e32 v37, v37
	v_exp_f32_e32 v40, v40
	v_exp_f32_e32 v41, v41
	v_exp_f32_e32 v34, v34
	v_exp_f32_e32 v35, v35
	v_cvt_pk_bf16_f32 v156, v44, v45
	v_cvt_pk_bf16_f32 v157, v46, v47
	v_cvt_pk_bf16_f32 v158, v48, v49
	v_cvt_pk_bf16_f32 v159, v50, v51
	v_cvt_pk_bf16_f32 v160, v54, v55
	v_cvt_pk_bf16_f32 v161, v58, v59
	v_cvt_pk_bf16_f32 v162, v64, v65
	v_cvt_pk_bf16_f32 v163, v56, v57
	v_cvt_pk_bf16_f32 v170, v62, v63
	v_cvt_pk_bf16_f32 v171, v52, v53
	v_cvt_pk_bf16_f32 v172, v60, v61
	v_cvt_pk_bf16_f32 v173, v38, v39
	v_cvt_pk_bf16_f32 v174, v42, v43
	v_cvt_pk_bf16_f32 v175, v36, v37
	v_cvt_pk_bf16_f32 v176, v40, v41
	v_cvt_pk_bf16_f32 v177, v34, v35
	s_waitcnt lgkmcnt(7)
	v_mfma_f32_32x32x16_bf16 v[18:33], v[110:113], v[156:159], v[18:33]
	s_waitcnt lgkmcnt(5)
	v_mfma_f32_32x32x16_bf16 v[2:17], v[132:135], v[156:159], v[2:17]
	v_mfma_f32_32x32x16_bf16 v[18:33], v[114:117], v[160:163], v[18:33]
	s_waitcnt lgkmcnt(4)
	v_mfma_f32_32x32x16_bf16 v[2:17], v[136:139], v[160:163], v[2:17]
	s_waitcnt lgkmcnt(3)
	v_mfma_f32_32x32x16_bf16 v[18:33], v[140:143], v[170:173], v[18:33]
	s_waitcnt lgkmcnt(2)
	v_mfma_f32_32x32x16_bf16 v[2:17], v[144:147], v[170:173], v[2:17]
	s_waitcnt lgkmcnt(1)
	v_mfma_f32_32x32x16_bf16 v[18:33], v[148:151], v[174:177], v[18:33]
	s_waitcnt lgkmcnt(0)
	v_mfma_f32_32x32x16_bf16 v[2:17], v[152:155], v[174:177], v[2:17]
	s_and_saveexec_b64 s[36:37], s[2:3]
	s_cbranch_execz .LBB0_545
	s_bitcmp1_b32 s47, 0
	s_cselect_b32 s2, 0x4900, 0
	v_add_u32_e32 v0, s2, v131
	v_add3_u32 v110, v0, v119, v104
	s_waitcnt vmcnt(3)
	ds_write_b128 v110, v[82:85]
	s_waitcnt vmcnt(2)
	ds_write_b128 v110, v[86:89] offset:4608
	v_sub_u32_e32 v186, v110, v187
	s_waitcnt vmcnt(1)
	ds_write_b64 v186, v[90:91] offset:9216
	ds_write_b64 v186, v[92:93] offset:9232
	s_waitcnt vmcnt(0)
	ds_write_b64 v186, v[94:95] offset:13824
	ds_write_b64 v186, v[96:97] offset:13840
	s_and_b64 exec, exec, s[0:1]
	s_cbranch_execz .LBB0_545
	v_mul_f32_e32 v118, 0x3fb8aa3b, v118
	v_lshl_add_u32 v0, v130, 2, v0
	ds_write_b32 v0, v118 offset:18432
	s_branch .LBB0_545
